# NA tile: V operands read ahead into dead registers (16 PV MFMAs behind two counted waits); rescale alpha LDS exchange overlapped with the exp block
# speedup vs baseline: 1.0081x; 1.0081x over previous
; template <bool DIFF> ...
;     ...
;     const bool active = DIFF || (t >= rstart && t < rstart + 8);
;     if (active) {
;       bf16x8 pa0, pa1, pa2, pa3;
;     ...
;       f32x16 a0, b0, a1, b1;
;       qkt<DIFF>(a0, b0, K_lds, Q_lds, r32, r32, hi);
;       qkt<DIFF>(a1, b1, K_lds, Q_lds, r32 + 32, r32, hi);
.LBB0_369:
	v_cmp_ge_u32_e32 vcc, s40, v159
	v_cmp_lt_u32_e64 s[40:41], s40, v160
	s_and_b64 s[88:89], vcc, s[40:41]
	s_and_saveexec_b64 s[40:41], s[88:89]
	s_cbranch_execz .LBB0_439
	v_add_u32_e32 v78, v161, v162
	ds_read_b128 v[66:69], v78
	ds_read_b128 v[70:73], v175 offset:36864
	v_add_u32_e32 v79, v161, v163
	ds_read_b128 v[74:77], v79
	ds_read_b128 v[82:85], v176 offset:36864
	v_add_u32_e32 v153, v161, v164
	v_add_u32_e32 v185, v161, v165
	s_waitcnt lgkmcnt(2)
	v_mfma_f32_32x32x16_bf16 v[98:113], v[66:69], v[70:73], 0
	ds_read_b128 v[66:69], v153
	ds_read_b128 v[186:189], v177 offset:36864
	v_add_u32_e32 v206, v161, v166
	v_add_u32_e32 v207, v161, v167
	v_add_u32_e32 v209, v161, v168
	v_add_u32_e32 v222, v161, v169
	s_waitcnt lgkmcnt(2)
	v_mfma_f32_32x32x16_bf16 v[114:129], v[74:77], v[82:85], 0
	ds_read_b128 v[74:77], v185
	ds_read_b128 v[190:193], v178 offset:36864
	s_waitcnt lgkmcnt(2)
	v_mfma_f32_32x32x16_bf16 v[98:113], v[66:69], v[186:189], v[98:113]
	ds_read_b128 v[66:69], v206
	ds_read_b128 v[194:197], v179 offset:36864
	s_waitcnt lgkmcnt(2)
	v_mfma_f32_32x32x16_bf16 v[114:129], v[74:77], v[190:193], v[114:129]
	ds_read_b128 v[74:77], v207
	ds_read_b128 v[198:201], v180 offset:36864
	s_waitcnt lgkmcnt(2)
	v_mfma_f32_32x32x16_bf16 v[98:113], v[66:69], v[194:197], v[98:113]
	ds_read_b128 v[66:69], v209
	ds_read_b128 v[202:205], v181 offset:36864
	s_waitcnt lgkmcnt(2)
	v_mfma_f32_32x32x16_bf16 v[114:129], v[74:77], v[198:201], v[114:129]
	ds_read_b128 v[74:77], v222
	ds_read_b128 v[210:213], v182 offset:36864
	s_waitcnt lgkmcnt(2)
	v_mfma_f32_32x32x16_bf16 v[98:113], v[66:69], v[202:205], v[98:113]
	ds_read_b128 v[66:69], v78 offset:8192
	ds_read_b128 v[86:89], v79 offset:8192
	ds_read_b128 v[214:217], v153 offset:8192
	ds_read_b128 v[218:221], v185 offset:8192
	s_waitcnt lgkmcnt(4)
	v_mfma_f32_32x32x16_bf16 v[114:129], v[74:77], v[210:213], v[114:129]
	s_waitcnt lgkmcnt(3)
	v_mfma_f32_32x32x16_bf16 v[66:81], v[66:69], v[70:73], 0
	s_waitcnt lgkmcnt(2)
	v_mfma_f32_32x32x16_bf16 v[82:97], v[86:89], v[82:85], 0
	s_waitcnt lgkmcnt(1)
	v_mfma_f32_32x32x16_bf16 v[66:81], v[214:217], v[186:189], v[66:81]
	s_waitcnt lgkmcnt(0)
	v_mfma_f32_32x32x16_bf16 v[82:97], v[218:221], v[190:193], v[82:97]
	ds_read_b128 v[186:189], v206 offset:8192
	ds_read_b128 v[190:193], v207 offset:8192
	s_waitcnt lgkmcnt(1)
	v_mfma_f32_32x32x16_bf16 v[66:81], v[186:189], v[194:197], v[66:81]
	s_waitcnt lgkmcnt(0)
	v_mfma_f32_32x32x16_bf16 v[82:97], v[190:193], v[198:201], v[82:97]
	ds_read_b128 v[186:189], v209 offset:8192
	ds_read_b128 v[190:193], v222 offset:8192
	s_waitcnt lgkmcnt(1)
	v_mfma_f32_32x32x16_bf16 v[66:81], v[186:189], v[202:205], v[66:81]
	s_waitcnt lgkmcnt(0)
	v_mfma_f32_32x32x16_bf16 v[82:97], v[190:193], v[210:213], v[82:97]
	ds_read_b32 v223, v170
	ds_read_b32 v224, v170 offset:4
	ds_read_b32 v225, v170 offset:8
	ds_read_b32 v226, v170 offset:12
	ds_read_b32 v227, v170 offset:32
	ds_read_b32 v228, v170 offset:36
	ds_read_b32 v229, v170 offset:40
	ds_read_b32 v230, v170 offset:44
	ds_read_b32 v231, v170 offset:64
	ds_read_b32 v232, v170 offset:68
	ds_read_b32 v233, v170 offset:72
	ds_read_b32 v234, v170 offset:76
	ds_read_b32 v235, v170 offset:96
	ds_read_b32 v236, v170 offset:100
	ds_read_b32 v237, v170 offset:104
	ds_read_b32 v238, v170 offset:108
	ds_read_b32 v239, v170 offset:128
	ds_read_b32 v240, v170 offset:132
	ds_read_b32 v241, v170 offset:136
	ds_read_b32 v242, v170 offset:140
	ds_read_b32 v243, v170 offset:160
	ds_read_b32 v244, v170 offset:164
	ds_read_b32 v245, v170 offset:168
	ds_read_b32 v246, v170 offset:172
	ds_read_b32 v247, v170 offset:192
	ds_read_b32 v248, v170 offset:196
	ds_read_b32 v249, v170 offset:200
	ds_read_b32 v250, v170 offset:204
	ds_read_b32 v251, v170 offset:224
	ds_read_b32 v252, v170 offset:228
	ds_read_b32 v253, v170 offset:232
	ds_read_b32 v254, v170 offset:236
	v_mov_b32_e32 v153, 0xf149f2ca
	v_mov_b32_e32 v185, 0xf149f2ca
	v_add_f32_e32 v98, v98, v114
	s_waitcnt lgkmcnt(15)
	v_add_f32_e32 v98, v98, v223
	v_cndmask_b32_e64 v185, v185, v98, s[4:5]
	v_add_f32_e32 v98, v99, v115
	s_waitcnt lgkmcnt(15)
	v_add_f32_e32 v98, v98, v224
	v_cndmask_b32_e64 v153, v153, v98, s[6:7]
	v_mov_b32_e32 v98, 0xf149f2ca
	v_mov_b32_e32 v99, 0xf149f2ca
	v_add_f32_e32 v100, v100, v116
	s_waitcnt lgkmcnt(15)
	v_add_f32_e32 v100, v100, v225
	v_cndmask_b32_e64 v99, v99, v100, s[8:9]
	v_add_f32_e32 v100, v101, v117
	s_waitcnt lgkmcnt(15)
	v_add_f32_e32 v100, v100, v226
	v_cndmask_b32_e64 v98, v98, v100, s[10:11]
	v_mov_b32_e32 v100, 0xf149f2ca
	v_mov_b32_e32 v101, 0xf149f2ca
	v_add_f32_e32 v102, v102, v118
	s_waitcnt lgkmcnt(15)
	v_add_f32_e32 v102, v102, v227
	v_cndmask_b32_e64 v101, v101, v102, s[12:13]
	v_add_f32_e32 v102, v103, v119
	s_waitcnt lgkmcnt(15)
	v_add_f32_e32 v102, v102, v228
	v_cndmask_b32_e64 v100, v100, v102, s[14:15]
	v_mov_b32_e32 v102, 0xf149f2ca
	v_mov_b32_e32 v103, 0xf149f2ca
	v_add_f32_e32 v104, v104, v120
	s_waitcnt lgkmcnt(15)
	v_add_f32_e32 v104, v104, v229
	v_cndmask_b32_e64 v103, v103, v104, s[16:17]
	v_add_f32_e32 v104, v105, v121
	s_waitcnt lgkmcnt(15)
	v_add_f32_e32 v104, v104, v230
	v_cndmask_b32_e64 v102, v102, v104, s[18:19]
	v_mov_b32_e32 v104, 0xf149f2ca
	v_mov_b32_e32 v105, 0xf149f2ca
	v_add_f32_e32 v106, v106, v122
	s_waitcnt lgkmcnt(15)
	v_add_f32_e32 v106, v106, v231
	v_cndmask_b32_e64 v105, v105, v106, s[54:55]
	v_add_f32_e32 v106, v107, v123
	s_waitcnt lgkmcnt(15)
	v_add_f32_e32 v106, v106, v232
	v_cndmask_b32_e64 v104, v104, v106, s[56:57]
	v_mov_b32_e32 v106, 0xf149f2ca
	v_mov_b32_e32 v107, 0xf149f2ca
	v_add_f32_e32 v108, v108, v124
	s_waitcnt lgkmcnt(15)
; template <bool DIFF> ...
;     ...
;         float mx = a0[0];
; #pragma unroll
;         for (int r = 1; r < 16; ++r) mx = fmaxf(mx, a0[r]);
; #pragma unroll
;         for (int r = 0; r < 16; ++r) mx = fmaxf(mx, a1[r]);
;         { auto rr = __builtin_amdgcn_permlane32_swap(__float_as_uint(mx), __float_as_uint(mx), false, false); mx = fmaxf(__uint_as_float(rr[0]), __uint_as_float(rr[1])); }
;         const float mn = fmaxf(m1, mx), alpha = __builtin_amdgcn_exp2f((m1 - mn) * C), x1 = -mn * C; m1 = mn;
;         float ps = 0.f;
; #pragma unroll
;         for (int r = 0; r < 16; ++r) { a0[r] = __builtin_amdgcn_exp2f(fmaf(a0[r], C, x1)); ps += a0[r]; }
; #pragma unroll
;         for (int r = 0; r < 16; ++r) { a1[r] = __builtin_amdgcn_exp2f(fmaf(a1[r], C, x1)); ps += a1[r]; }
;         l1 = l1 * alpha + ps;
;         if (__any(alpha < 1.0f)) {
	v_add_f32_e32 v108, v108, v233
	v_cndmask_b32_e64 v107, v107, v108, s[58:59]
	v_add_f32_e32 v108, v109, v125
	s_waitcnt lgkmcnt(15)
	v_add_f32_e32 v108, v108, v234
	v_cndmask_b32_e64 v106, v106, v108, s[60:61]
	v_mov_b32_e32 v108, 0xf149f2ca
	v_mov_b32_e32 v109, 0xf149f2ca
	v_add_f32_e32 v110, v110, v126
	s_waitcnt lgkmcnt(15)
	v_add_f32_e32 v110, v110, v235
	v_cndmask_b32_e64 v109, v109, v110, s[62:63]
	v_add_f32_e32 v110, v111, v127
	s_waitcnt lgkmcnt(15)
	v_add_f32_e32 v110, v110, v236
	v_cndmask_b32_e64 v108, v108, v110, s[64:65]
	v_mov_b32_e32 v110, 0xf149f2ca
	v_mov_b32_e32 v111, 0xf149f2ca
	v_add_f32_e32 v112, v112, v128
	s_waitcnt lgkmcnt(15)
	v_add_f32_e32 v112, v112, v237
	v_cndmask_b32_e64 v111, v111, v112, s[66:67]
	v_add_f32_e32 v112, v113, v129
	s_waitcnt lgkmcnt(15)
	v_add_f32_e32 v112, v112, v238
	v_cndmask_b32_e64 v110, v110, v112, s[68:69]
	v_mov_b32_e32 v112, 0xf149f2ca
	v_mov_b32_e32 v113, 0xf149f2ca
	v_add_f32_e32 v66, v66, v82
	s_waitcnt lgkmcnt(15)
	v_add_f32_e32 v66, v66, v239
	v_cndmask_b32_e64 v113, v113, v66, s[70:71]
	v_add_f32_e32 v66, v67, v83
	s_waitcnt lgkmcnt(14)
	v_add_f32_e32 v66, v66, v240
	v_cndmask_b32_e64 v112, v112, v66, s[72:73]
	v_mov_b32_e32 v66, 0xf149f2ca
	v_mov_b32_e32 v67, 0xf149f2ca
	v_add_f32_e32 v68, v68, v84
	s_waitcnt lgkmcnt(13)
	v_add_f32_e32 v68, v68, v241
	v_cndmask_b32_e64 v67, v67, v68, s[74:75]
	v_add_f32_e32 v68, v69, v85
	s_waitcnt lgkmcnt(12)
	v_add_f32_e32 v68, v68, v242
	v_cndmask_b32_e64 v66, v66, v68, s[76:77]
	v_mov_b32_e32 v69, 0xf149f2ca
	v_mov_b32_e32 v82, 0xf149f2ca
	v_add_f32_e32 v68, v70, v86
	s_waitcnt lgkmcnt(11)
	v_add_f32_e32 v68, v68, v243
	v_cndmask_b32_e64 v82, v82, v68, s[78:79]
	v_add_f32_e32 v68, v71, v87
	s_waitcnt lgkmcnt(10)
	v_add_f32_e32 v68, v68, v244
	v_cndmask_b32_e64 v69, v69, v68, s[80:81]
	v_mov_b32_e32 v70, 0xf149f2ca
	v_mov_b32_e32 v71, 0xf149f2ca
	v_add_f32_e32 v68, v72, v88
	s_waitcnt lgkmcnt(9)
	v_add_f32_e32 v68, v68, v245
	v_cndmask_b32_e64 v71, v71, v68, s[82:83]
	v_add_f32_e32 v68, v73, v89
	s_waitcnt lgkmcnt(8)
	v_add_f32_e32 v68, v68, v246
	v_cndmask_b32_e64 v70, v70, v68, s[84:85]
	v_mov_b32_e32 v72, 0xf149f2ca
	v_mov_b32_e32 v73, 0xf149f2ca
	v_add_f32_e32 v68, v74, v90
	s_waitcnt lgkmcnt(7)
	v_add_f32_e32 v68, v68, v247
	v_cndmask_b32_e64 v73, v73, v68, s[20:21]
	v_add_f32_e32 v68, v75, v91
	s_waitcnt lgkmcnt(6)
	v_add_f32_e32 v68, v68, v248
	v_cndmask_b32_e64 v72, v72, v68, s[22:23]
	v_mov_b32_e32 v74, 0xf149f2ca
	v_mov_b32_e32 v75, 0xf149f2ca
	v_add_f32_e32 v68, v76, v92
	s_waitcnt lgkmcnt(5)
	v_add_f32_e32 v68, v68, v249
	v_cndmask_b32_e64 v75, v75, v68, s[24:25]
	v_add_f32_e32 v68, v77, v93
	s_waitcnt lgkmcnt(4)
	v_add_f32_e32 v68, v68, v250
	v_cndmask_b32_e64 v74, v74, v68, s[26:27]
	v_mov_b32_e32 v76, 0xf149f2ca
	v_mov_b32_e32 v77, 0xf149f2ca
	v_add_f32_e32 v68, v78, v94
	s_waitcnt lgkmcnt(3)
	v_add_f32_e32 v68, v68, v251
	v_cndmask_b32_e64 v77, v77, v68, s[28:29]
	v_add_f32_e32 v68, v79, v95
	s_waitcnt lgkmcnt(2)
	v_add_f32_e32 v68, v68, v252
	v_cndmask_b32_e64 v76, v76, v68, s[30:31]
	v_mov_b32_e32 v78, 0xf149f2ca
	v_mov_b32_e32 v79, 0xf149f2ca
	v_add_f32_e32 v68, v80, v96
	s_waitcnt lgkmcnt(1)
	v_add_f32_e32 v68, v68, v253
	v_cndmask_b32_e64 v79, v79, v68, s[34:35]
	v_add_f32_e32 v68, v81, v97
	s_waitcnt lgkmcnt(0)
	v_add_f32_e32 v68, v68, v254
	v_cndmask_b32_e64 v78, v78, v68, s[36:37]
	v_max_f32_e32 v68, v153, v153
	v_max_f32_e32 v80, v185, v185
	v_max_f32_e32 v68, v80, v68
	v_max3_f32 v68, v68, v99, v98
	v_max3_f32 v68, v68, v101, v100
	v_max3_f32 v68, v68, v103, v102
	v_max3_f32 v68, v68, v105, v104
	v_max3_f32 v68, v68, v107, v106
	v_max3_f32 v68, v68, v109, v108
	v_max3_f32 v68, v68, v111, v110
	v_max3_f32 v68, v68, v113, v112
	v_max3_f32 v68, v68, v67, v66
	v_max3_f32 v68, v68, v82, v69
	v_max3_f32 v68, v68, v71, v70
	v_max3_f32 v68, v68, v73, v72
	v_max3_f32 v68, v68, v75, v74
	v_max3_f32 v68, v68, v77, v76
	v_max3_f32 v68, v68, v79, v78
	v_mov_b32_e32 v80, v68
	s_nop 1
	v_permlane32_swap_b32_e32 v68, v80
	v_max3_f32 v68, v184, v68, v80
	v_sub_f32_e32 v80, v184, v68
	v_mul_f32_e32 v80, 0x3e0293ee, v80
	v_exp_f32_e32 v80, v80
	s_nop 0
	v_cmp_gt_f32_e32 vcc, 1.0, v80
	s_mov_b32 s32, 0
	s_cbranch_vccz .LBB0_438
	s_mov_b32 s32, 1
	s_and_saveexec_b64 s[88:89], s[38:39]
	ds_write_b32 v157, v80 offset:34816
	s_or_b64 exec, exec, s[88:89]
	s_waitcnt lgkmcnt(0)
	v_add_u32_e32 v81, v156, v0
	ds_read_b128 v[118:121], v81 offset:34912
	ds_read_b128 v[122:125], v81 offset:34880
	ds_read_b128 v[126:129], v81 offset:34848
	ds_read_b128 v[114:117], v81 offset:34816
; __device__ __forceinline__ int crow(int r, int hi) { return (r & 3) + 8 * (r >> 2) + 4 * hi; }
; template <bool DIFF> ...
;     ...
;         for (int r = 0; r < 16; ++r) { a0[r] = __builtin_amdgcn_exp2f(fmaf(a0[r], C, x1)); ps += a0[r]; }
; #pragma unroll
;         for (int r = 0; r < 16; ++r) { a1[r] = __builtin_amdgcn_exp2f(fmaf(a1[r], C, x1)); ps += a1[r]; }
;         l1 = l1 * alpha + ps;
;         if (__any(alpha < 1.0f)) {
;           if (hi == 0) wsc[r32] = alpha;
;           asm volatile("s_waitcnt lgkmcnt(0)" ::: "memory");
; #pragma unroll
;           for (int r = 0; r < 16; ++r) { const float al = wsc[crow(r, hi)];
; #pragma unroll
;             for (int d = 0; d < 4; ++d) o[d][r] *= al; }
;         }
;         PK4(a0, 0, pa0); PK4(a0, 8, pa1); PK4(a1, 0, pa2); PK4(a1, 8, pa3);
.LBB0_438:
	ds_read_b64_tr_b16 v[210:211], v158 offset:0x1000
	ds_read_b64_tr_b16 v[212:213], v158 offset:0x1800
	ds_read_b64_tr_b16 v[214:215], v158 offset:0x1200
	ds_read_b64_tr_b16 v[216:217], v158 offset:0x1a00
	ds_read_b64_tr_b16 v[218:219], v158 offset:0x1400
	ds_read_b64_tr_b16 v[220:221], v158 offset:0x1c00
	ds_read_b64_tr_b16 v[222:223], v158 offset:0x1600
	ds_read_b64_tr_b16 v[224:225], v158 offset:0x1e00
	ds_read_b64_tr_b16 v[234:235], v158 offset:0x2000
	ds_read_b64_tr_b16 v[236:237], v158 offset:0x2800
	ds_read_b64_tr_b16 v[238:239], v158 offset:0x2200
	ds_read_b64_tr_b16 v[240:241], v158 offset:0x2a00
	ds_read_b64_tr_b16 v[242:243], v158 offset:0x2400
	ds_read_b64_tr_b16 v[244:245], v158 offset:0x2c00
	ds_read_b64_tr_b16 v[246:247], v158 offset:0x2600
	ds_read_b64_tr_b16 v[248:249], v158 offset:0x2e00
	v_mul_f32_e32 v81, 0xbe0293ee, v68
	v_fmamk_f32 v83, v185, 0x3e0293ee, v81
	v_exp_f32_e32 v83, v83
	v_fmamk_f32 v84, v153, 0x3e0293ee, v81
	v_exp_f32_e32 v84, v84
	v_fmamk_f32 v85, v99, 0x3e0293ee, v81
	v_exp_f32_e32 v85, v85
	v_fmamk_f32 v86, v98, 0x3e0293ee, v81
	v_exp_f32_e32 v86, v86
	v_fmamk_f32 v88, v101, 0x3e0293ee, v81
	v_add_f32_e32 v87, 0, v83
	v_exp_f32_e32 v88, v88
	v_fmamk_f32 v89, v100, 0x3e0293ee, v81
	v_add_f32_e32 v87, v84, v87
	v_exp_f32_e32 v89, v89
	v_fmamk_f32 v90, v103, 0x3e0293ee, v81
	v_add_f32_e32 v87, v85, v87
	v_exp_f32_e32 v90, v90
	v_fmamk_f32 v91, v102, 0x3e0293ee, v81
	v_add_f32_e32 v87, v86, v87
	v_exp_f32_e32 v91, v91
	v_fmamk_f32 v92, v105, 0x3e0293ee, v81
	v_add_f32_e32 v87, v88, v87
	v_exp_f32_e32 v92, v92
	v_fmamk_f32 v93, v104, 0x3e0293ee, v81
	v_add_f32_e32 v87, v89, v87
	v_exp_f32_e32 v93, v93
	v_fmamk_f32 v94, v107, 0x3e0293ee, v81
	v_add_f32_e32 v87, v90, v87
	v_exp_f32_e32 v94, v94
	v_fmamk_f32 v95, v106, 0x3e0293ee, v81
	v_add_f32_e32 v87, v91, v87
	v_exp_f32_e32 v95, v95
	v_fmamk_f32 v96, v109, 0x3e0293ee, v81
	v_add_f32_e32 v87, v92, v87
	v_exp_f32_e32 v96, v96
	v_fmamk_f32 v97, v108, 0x3e0293ee, v81
	v_add_f32_e32 v87, v93, v87
	v_exp_f32_e32 v97, v97
	v_fmamk_f32 v98, v111, 0x3e0293ee, v81
	v_add_f32_e32 v87, v94, v87
	v_exp_f32_e32 v98, v98
	v_fmamk_f32 v99, v110, 0x3e0293ee, v81
	v_add_f32_e32 v87, v95, v87
	v_exp_f32_e32 v99, v99
	v_fmamk_f32 v100, v113, 0x3e0293ee, v81
	v_add_f32_e32 v87, v96, v87
	v_exp_f32_e32 v100, v100
	v_fmamk_f32 v101, v112, 0x3e0293ee, v81
	v_add_f32_e32 v87, v97, v87
	v_exp_f32_e32 v101, v101
	v_fmamk_f32 v67, v67, 0x3e0293ee, v81
	v_add_f32_e32 v87, v98, v87
	v_exp_f32_e32 v67, v67
	v_fmamk_f32 v66, v66, 0x3e0293ee, v81
	v_add_f32_e32 v87, v99, v87
	v_exp_f32_e32 v66, v66
	v_fmamk_f32 v82, v82, 0x3e0293ee, v81
	v_add_f32_e32 v87, v100, v87
	v_exp_f32_e32 v82, v82
	v_fmamk_f32 v69, v69, 0x3e0293ee, v81
	v_add_f32_e32 v87, v101, v87
	v_exp_f32_e32 v69, v69
	v_fmamk_f32 v71, v71, 0x3e0293ee, v81
	v_add_f32_e32 v87, v67, v87
	v_exp_f32_e32 v102, v71
	v_fmamk_f32 v70, v70, 0x3e0293ee, v81
	v_add_f32_e32 v87, v66, v87
	v_exp_f32_e32 v103, v70
	v_fmamk_f32 v71, v73, 0x3e0293ee, v81
	v_add_f32_e32 v70, v82, v87
	v_exp_f32_e32 v87, v71
	v_fmamk_f32 v71, v72, 0x3e0293ee, v81
	v_add_f32_e32 v70, v69, v70
	v_exp_f32_e32 v104, v71
	v_fmamk_f32 v71, v75, 0x3e0293ee, v81
	v_add_f32_e32 v70, v102, v70
	v_exp_f32_e32 v105, v71
	v_fmamk_f32 v71, v74, 0x3e0293ee, v81
	v_add_f32_e32 v70, v103, v70
	v_exp_f32_e32 v106, v71
	v_fmamk_f32 v71, v77, 0x3e0293ee, v81
	v_add_f32_e32 v70, v87, v70
	v_exp_f32_e32 v107, v71
	v_fmamk_f32 v71, v76, 0x3e0293ee, v81
	v_add_f32_e32 v70, v104, v70
	v_exp_f32_e32 v108, v71
	v_fmamk_f32 v71, v79, 0x3e0293ee, v81
	v_add_f32_e32 v70, v105, v70
	v_exp_f32_e32 v109, v71
	v_fmac_f32_e32 v81, 0x3e0293ee, v78
	v_add_f32_e32 v70, v106, v70
	v_exp_f32_e32 v110, v81
	v_add_f32_e32 v70, v107, v70
	v_add_f32_e32 v70, v108, v70
	v_add_f32_e32 v70, v109, v70
	v_add_f32_e32 v111, v110, v70
	v_fmac_f32_e32 v111, v183, v80
	v_cvt_pk_bf16_f32 v70, v83, v84
	v_cvt_pk_bf16_f32 v71, v85, v86
	v_cvt_pk_bf16_f32 v72, v88, v89
	v_cvt_pk_bf16_f32 v73, v90, v91
	v_cvt_pk_bf16_f32 v74, v92, v93
	v_cvt_pk_bf16_f32 v75, v94, v95
	v_cvt_pk_bf16_f32 v76, v96, v97
	v_cvt_pk_bf16_f32 v77, v98, v99
	v_cvt_pk_bf16_f32 v78, v100, v101
	v_cvt_pk_bf16_f32 v79, v67, v66
	v_cvt_pk_bf16_f32 v80, v82, v69
	v_cvt_pk_bf16_f32 v81, v102, v103
	v_cvt_pk_bf16_f32 v82, v87, v104
	ds_read_b64_tr_b16 v[86:87], v158 offset:0
	ds_read_b64_tr_b16 v[88:89], v158 offset:0x800
	ds_read_b64_tr_b16 v[90:91], v158 offset:0x200
	ds_read_b64_tr_b16 v[92:93], v158 offset:0xa00
	ds_read_b64_tr_b16 v[94:95], v158 offset:0x400
	ds_read_b64_tr_b16 v[96:97], v158 offset:0xc00
	ds_read_b64_tr_b16 v[98:99], v158 offset:0x600
	ds_read_b64_tr_b16 v[100:101], v158 offset:0xe00
	v_cvt_pk_bf16_f32 v83, v105, v106
	v_cvt_pk_bf16_f32 v84, v107, v108
	v_cvt_pk_bf16_f32 v85, v109, v110
	v_permlane32_swap_b32_e32 v70, v72
	v_permlane32_swap_b32_e32 v71, v73
	v_permlane32_swap_b32_e32 v74, v76
	v_permlane32_swap_b32_e32 v75, v77
	v_permlane32_swap_b32_e32 v78, v80
	v_permlane32_swap_b32_e32 v79, v81
	v_permlane32_swap_b32_e32 v82, v84
	v_permlane32_swap_b32_e32 v83, v85
	s_cmp_eq_u32 s32, 0
	s_cbranch_scc1 .Lna_rs_done
	s_waitcnt lgkmcnt(8)
	v_pk_mul_f32 v[62:63], v[62:63], v[118:119]
	v_pk_mul_f32 v[58:59], v[58:59], v[122:123]
	v_pk_mul_f32 v[54:55], v[54:55], v[126:127]
	v_pk_mul_f32 v[64:65], v[64:65], v[120:121]
	v_pk_mul_f32 v[60:61], v[60:61], v[124:125]
	v_pk_mul_f32 v[56:57], v[56:57], v[128:129]
	v_pk_mul_f32 v[52:53], v[52:53], v[116:117]
	v_pk_mul_f32 v[50:51], v[50:51], v[114:115]
	v_pk_mul_f32 v[46:47], v[46:47], v[118:119]
	v_pk_mul_f32 v[42:43], v[42:43], v[122:123]
	v_pk_mul_f32 v[38:39], v[38:39], v[126:127]
	v_pk_mul_f32 v[48:49], v[48:49], v[120:121]
	v_pk_mul_f32 v[44:45], v[44:45], v[124:125]
	v_pk_mul_f32 v[40:41], v[40:41], v[128:129]
	v_pk_mul_f32 v[36:37], v[36:37], v[116:117]
	v_pk_mul_f32 v[34:35], v[34:35], v[114:115]
	v_pk_mul_f32 v[30:31], v[30:31], v[118:119]
	v_pk_mul_f32 v[26:27], v[26:27], v[122:123]
	v_pk_mul_f32 v[22:23], v[22:23], v[126:127]
	v_pk_mul_f32 v[32:33], v[32:33], v[120:121]
	v_pk_mul_f32 v[28:29], v[28:29], v[124:125]
	v_pk_mul_f32 v[24:25], v[24:25], v[128:129]
	v_pk_mul_f32 v[20:21], v[20:21], v[116:117]
	v_pk_mul_f32 v[18:19], v[18:19], v[114:115]
	v_pk_mul_f32 v[14:15], v[14:15], v[118:119]
	v_pk_mul_f32 v[10:11], v[10:11], v[122:123]
	v_pk_mul_f32 v[6:7], v[6:7], v[126:127]
	v_pk_mul_f32 v[16:17], v[16:17], v[120:121]
	v_pk_mul_f32 v[12:13], v[12:13], v[124:125]
	v_pk_mul_f32 v[8:9], v[8:9], v[128:129]
	v_pk_mul_f32 v[4:5], v[4:5], v[116:117]
	v_pk_mul_f32 v[2:3], v[2:3], v[114:115]
; #define SBAR() __builtin_amdgcn_sched_barrier(0)
; template <int KS> __device__ __forceinline__ void pv_step(f32x16* o, int vb, bf16x8 pa) {
;   const s16x4 l0 = tr_read<v_rd_off(0, KS, 0)>(vb), h0 = tr_read<v_rd_off(0, KS, 1)>(vb), l1 = tr_read<v_rd_off(1, KS, 0)>(vb), h1 = tr_read<v_rd_off(1, KS, 1)>(vb);
;   const s16x4 l2 = tr_read<v_rd_off(2, KS, 0)>(vb), h2 = tr_read<v_rd_off(2, KS, 1)>(vb), l3 = tr_read<v_rd_off(3, KS, 0)>(vb), h3 = tr_read<v_rd_off(3, KS, 1)>(vb);
;   asm volatile("s_waitcnt lgkmcnt(0)" ::: "memory"); SBAR();
;     ...
;   o[0] = __builtin_amdgcn_mfma_f32_32x32x16_bf16(pa, PK(l0, h0), o[0], 0, 0, 0);
;   o[1] = __builtin_amdgcn_mfma_f32_32x32x16_bf16(pa, PK(l1, h1), o[1], 0, 0, 0);
;   o[2] = __builtin_amdgcn_mfma_f32_32x32x16_bf16(pa, PK(l2, h2), o[2], 0, 0, 0);
;   o[3] = __builtin_amdgcn_mfma_f32_32x32x16_bf16(pa, PK(l3, h3), o[3], 0, 0, 0);
;     ...
; }
; template <bool DIFF> ...
;     ...
;         pv_step<0>(o, vb0, pa0); pv_step<1>(o, vb0, pa1); pv_step<2>(o, vb0, pa2); pv_step<3>(o, vb0, pa3);
.Lna_rs_done:
	ds_read_b64_tr_b16 v[114:115], v158 offset:0x3000
	ds_read_b64_tr_b16 v[116:117], v158 offset:0x3800
	ds_read_b64_tr_b16 v[118:119], v158 offset:0x3200
	ds_read_b64_tr_b16 v[120:121], v158 offset:0x3a00
	ds_read_b64_tr_b16 v[122:123], v158 offset:0x3400
	ds_read_b64_tr_b16 v[124:125], v158 offset:0x3c00
	ds_read_b64_tr_b16 v[126:127], v158 offset:0x3600
	ds_read_b64_tr_b16 v[128:129], v158 offset:0x3e00
	s_waitcnt lgkmcnt(8)
	v_mfma_f32_32x32x16_bf16 v[50:65], v[70:73], v[86:89], v[50:65]
	v_mfma_f32_32x32x16_bf16 v[34:49], v[70:73], v[90:93], v[34:49]
	v_mfma_f32_32x32x16_bf16 v[18:33], v[70:73], v[94:97], v[18:33]
	v_mfma_f32_32x32x16_bf16 v[2:17], v[70:73], v[98:101], v[2:17]
	v_mfma_f32_32x32x16_bf16 v[50:65], v[74:77], v[210:213], v[50:65]
	v_mfma_f32_32x32x16_bf16 v[34:49], v[74:77], v[214:217], v[34:49]
	v_mfma_f32_32x32x16_bf16 v[18:33], v[74:77], v[218:221], v[18:33]
	v_mfma_f32_32x32x16_bf16 v[2:17], v[74:77], v[222:225], v[2:17]
	v_mfma_f32_32x32x16_bf16 v[50:65], v[78:81], v[234:237], v[50:65]
	v_mfma_f32_32x32x16_bf16 v[34:49], v[78:81], v[238:241], v[34:49]
	v_mfma_f32_32x32x16_bf16 v[18:33], v[78:81], v[242:245], v[18:33]
	v_mfma_f32_32x32x16_bf16 v[2:17], v[78:81], v[246:249], v[2:17]
	s_waitcnt lgkmcnt(0)
	v_mfma_f32_32x32x16_bf16 v[50:65], v[82:85], v[114:117], v[50:65]
	v_mov_b32_e32 v184, v68
	v_mov_b32_e32 v183, v111
	v_mfma_f32_32x32x16_bf16 v[34:49], v[82:85], v[118:121], v[34:49]
	v_mfma_f32_32x32x16_bf16 v[18:33], v[82:85], v[122:125], v[18:33]
	v_mfma_f32_32x32x16_bf16 v[2:17], v[82:85], v[126:129], v[2:17]
